# 4 barrier phases per K-step main loop + plain GEMM1 tiles: epilogue of the ai=0 accumulator blocks runs inside the last K-step's load segment (overlapped with the partner half's MFMAs), boundary epilo
# speedup vs baseline: 1.0054x; 1.0054x over previous
; template <class Epi>
; __device__ __forceinline__ void gemm_phase(LAS unsigned char* lds, const Gemm g, const StaticOrder& S, const Epi& E) {
;     ...
;     for (;;) {
;         const bool has_next = S.next(ui + 1, nxt);
;         const char* nA = has_next ? (const char*)g.A + (size_t)nxt.pm * tstepA : cA; const char* nB = has_next ? (const char*)g.Bt + (size_t)nxt.pn * tstepB : cB;
;         for (int t = 0; t < nt; t += 2) {
;             const bool last = (t == nt - 2);
;             const char* a1 = cA + (size_t)(t + 1) * kstep;
;             const char* a2 = last ? nA : cA + (size_t)(t + 2) * kstep; const char* b2 = last ? nB : cB + (size_t)(t + 2) * kstep;
;             const char* a3 = a2 + kstep; const char* b3 = b2 + kstep;
;     ...
; #pragma unroll
;         for (int a = 0; a < 2; ++a)
; #pragma unroll
;             for (int b = 0; b < 2; ++b)
; #pragma unroll
;                 for (int m = 0; m < 4; ++m)
; #pragma unroll
;                     for (int n = 0; n < 2; ++n) acc[a][b][m][n] = (f32x4){0.f, 0.f, 0.f, 0.f};
;         cur = nxt; cA = nA; cB = nB; ++ui;
.LBB0_115:
	s_cmp_lt_u32 s48, 9
	s_cselect_b32 s32, 1, 0
	s_cmp_eq_u32 s1, 0
	s_cselect_b32 s32, s32, 0
	s_lshl_b32 s34, s20, 8
	s_lshl_b32 s20, s68, 8
	s_and_b32 s20, s20, 0x100
	s_lshl_b32 s44, s20, 2
	s_ashr_i32 s35, s34, 31
	s_add_i32 s68, s18, s44
	s_add_u32 s36, s36, 0x80
	s_addc_u32 s37, s37, 0
	s_add_u32 s69, s70, 0x100
	v_mov_b32_e32 v0, 0
	s_addc_u32 s70, s71, 0
	s_mov_b32 s44, 0
	v_mov_b32_e32 v1, v0
	v_mov_b32_e32 v2, v0
	v_mov_b32_e32 v3, v0
	v_mov_b32_e32 v4, v0
	v_mov_b32_e32 v5, v0
	v_mov_b32_e32 v6, v0
	v_mov_b32_e32 v7, v0
	v_mov_b32_e32 v8, v0
	v_mov_b32_e32 v9, v0
	v_mov_b32_e32 v10, v0
	v_mov_b32_e32 v11, v0
	v_mov_b32_e32 v16, v0
	v_mov_b32_e32 v17, v0
	v_mov_b32_e32 v18, v0
	v_mov_b32_e32 v19, v0
	v_mov_b32_e32 v24, v0
	v_mov_b32_e32 v25, v0
	v_mov_b32_e32 v26, v0
	v_mov_b32_e32 v27, v0
	v_mov_b32_e32 v32, v0
	v_mov_b32_e32 v33, v0
	v_mov_b32_e32 v34, v0
	v_mov_b32_e32 v35, v0
	v_mov_b32_e32 v40, v0
	v_mov_b32_e32 v41, v0
	v_mov_b32_e32 v42, v0
	v_mov_b32_e32 v43, v0
	v_mov_b32_e32 v48, v0
	v_mov_b32_e32 v49, v0
	v_mov_b32_e32 v50, v0
	v_mov_b32_e32 v51, v0
	v_mov_b32_e32 v12, v0
	v_mov_b32_e32 v13, v0
	v_mov_b32_e32 v14, v0
	v_mov_b32_e32 v15, v0
	v_mov_b32_e32 v20, v0
	v_mov_b32_e32 v21, v0
	v_mov_b32_e32 v22, v0
	v_mov_b32_e32 v23, v0
	v_mov_b32_e32 v28, v0
	v_mov_b32_e32 v29, v0
	v_mov_b32_e32 v30, v0
	v_mov_b32_e32 v31, v0
	v_mov_b32_e32 v36, v0
	v_mov_b32_e32 v37, v0
	v_mov_b32_e32 v38, v0
	v_mov_b32_e32 v39, v0
	v_mov_b32_e32 v44, v0
	v_mov_b32_e32 v45, v0
	v_mov_b32_e32 v46, v0
	v_mov_b32_e32 v47, v0
	v_mov_b32_e32 v52, v0
	v_mov_b32_e32 v53, v0
	v_mov_b32_e32 v54, v0
	v_mov_b32_e32 v55, v0
	v_mov_b32_e32 v56, v0
	v_mov_b32_e32 v57, v0
	v_mov_b32_e32 v58, v0
	v_mov_b32_e32 v59, v0
	v_mov_b32_e32 v60, v0
	v_mov_b32_e32 v61, v0
	v_mov_b32_e32 v62, v0
	v_mov_b32_e32 v63, v0
	v_mov_b32_e32 v64, v0
	v_mov_b32_e32 v65, v0
	v_mov_b32_e32 v66, v0
	v_mov_b32_e32 v67, v0
	v_mov_b32_e32 v68, v0
	v_mov_b32_e32 v69, v0
	v_mov_b32_e32 v70, v0
	v_mov_b32_e32 v71, v0
	v_mov_b32_e32 v76, v0
	v_mov_b32_e32 v77, v0
	v_mov_b32_e32 v78, v0
	v_mov_b32_e32 v79, v0
	v_mov_b32_e32 v84, v0
	v_mov_b32_e32 v85, v0
	v_mov_b32_e32 v86, v0
	v_mov_b32_e32 v87, v0
	v_mov_b32_e32 v92, v0
	v_mov_b32_e32 v93, v0
	v_mov_b32_e32 v94, v0
	v_mov_b32_e32 v95, v0
	v_mov_b32_e32 v100, v0
	v_mov_b32_e32 v101, v0
	v_mov_b32_e32 v102, v0
	v_mov_b32_e32 v103, v0
	v_mov_b32_e32 v108, v0
	v_mov_b32_e32 v109, v0
	v_mov_b32_e32 v110, v0
	v_mov_b32_e32 v111, v0
	v_mov_b32_e32 v116, v0
	v_mov_b32_e32 v117, v0
	v_mov_b32_e32 v118, v0
	v_mov_b32_e32 v119, v0
	v_mov_b32_e32 v72, v0
	v_mov_b32_e32 v73, v0
	v_mov_b32_e32 v74, v0
	v_mov_b32_e32 v75, v0
	v_mov_b32_e32 v80, v0
	v_mov_b32_e32 v81, v0
	v_mov_b32_e32 v82, v0
	v_mov_b32_e32 v83, v0
	v_mov_b32_e32 v88, v0
	v_mov_b32_e32 v89, v0
	v_mov_b32_e32 v90, v0
	v_mov_b32_e32 v91, v0
	v_mov_b32_e32 v96, v0
	v_mov_b32_e32 v97, v0
	v_mov_b32_e32 v98, v0
	v_mov_b32_e32 v99, v0
	v_mov_b32_e32 v104, v0
	v_mov_b32_e32 v105, v0
	v_mov_b32_e32 v106, v0
	v_mov_b32_e32 v107, v0
	v_mov_b32_e32 v112, v0
	v_mov_b32_e32 v113, v0
	v_mov_b32_e32 v114, v0
	v_mov_b32_e32 v115, v0
	v_mov_b32_e32 v120, v0
	v_mov_b32_e32 v121, v0
	v_mov_b32_e32 v122, v0
	v_mov_b32_e32 v123, v0
	v_mov_b32_e32 v124, v0
	v_mov_b32_e32 v125, v0
	v_mov_b32_e32 v126, v0
	v_mov_b32_e32 v127, v0
	s_waitcnt lgkmcnt(0)
	v_lshl_add_u64 v[128:129], s[34:35], 2, v[180:181]
	s_cmp_lt_u32 s75, 2
	s_cbranch_scc1 .Lresync_y
	s_cmpk_lt_u32 s79, 0x100
	s_cbranch_scc1 .Lresync_y
	s_barrier

; #define PG8_STAGE(bufoff, gbase, voff) do { _Pragma("unroll") for (int _i = 0; _i < 2; ++_i) \
;         __builtin_amdgcn_global_load_lds((const unsigned*)((const char*)(gbase) + (voff)[_i]), (LAS unsigned*)(lds + (bufoff) + ldsw + _i * 8192), 16, 0, 0); } while (0)
; #define PG8_LDA(dst, b, h) do { _Pragma("unroll") for (int m = 0; m < 4; ++m) _Pragma("unroll") for (int k = 0; k < 2; ++k) dst[m][k] = *(const LAS bf16x8*)(lds + PG8_SA(b, h) + aoff + m * 2048 + k * 1024); } while (0)
; #define PG8_LDB(dst, b, h) do { _Pragma("unroll") for (int n = 0; n < 2; ++n) _Pragma("unroll") for (int k = 0; k < 2; ++k) dst[n][k] = *(const LAS bf16x8*)(lds + PG8_SB(b, h) + boff + n * 2048 + k * 1024); } while (0)
; #define PG8_MMA(ai, bj, At, Bt) do { __builtin_amdgcn_s_setprio(1); _Pragma("unroll") for (int m = 0; m < 4; ++m) _Pragma("unroll") for (int n = 0; n < 2; ++n) _Pragma("unroll") for (int k = 0; k < 2; ++k) \
;         acc[ai][bj][m][n] = __builtin_amdgcn_mfma_f32_16x16x32_bf16(Bt[n][k], At[m][k], acc[ai][bj][m][n], 0, 0, 0); __builtin_amdgcn_s_setprio(0); } while (0)
; #define PG8_WAIT_V(n) asm volatile("s_waitcnt vmcnt(" #n ")" ::: "memory")
; #define PG8_WAIT_L(n) asm volatile("s_waitcnt lgkmcnt(" #n ")" ::: "memory")
; #define PG8_BAR __builtin_amdgcn_s_barrier()
; #define PG8_SCHED __builtin_amdgcn_sched_barrier(0)
; template <class Epi>
; __device__ __forceinline__ void gemm_phase(LAS unsigned char* lds, const Gemm g, const StaticOrder& S, const Epi& E) {
;     ...
;             PG8_LDB(B0, 0, 0); PG8_SCHED; PG8_LDA(At, 0, 0); PG8_STAGE(PG8_SA(1, 1), a1 + hstepA, voffA);
;             PG8_WAIT_L(8); PG8_BAR; PG8_WAIT_L(0); PG8_MMA(0, 0, At, B0); PG8_BAR; PG8_SCHED;
;             PG8_LDB(B1, 0, 1); PG8_STAGE(PG8_SB(0, 0), b2, voffB);
;             PG8_BAR; PG8_WAIT_L(0); PG8_MMA(0, 1, At, B1); PG8_BAR;
;             PG8_LDA(At, 0, 1); PG8_STAGE(PG8_SA(0, 0), a2, voffA);
;             PG8_BAR; PG8_WAIT_L(0); PG8_MMA(1, 0, At, B0); PG8_BAR; PG8_SCHED;
;             PG8_STAGE(PG8_SB(0, 1), b2 + hstepB, voffB);
;             PG8_WAIT_V(6); PG8_BAR; PG8_MMA(1, 1, At, B1); PG8_BAR;
.LBB0_116:
	s_add_i32 s35, s44, 2
	s_add_u32 s46, s36, 0x80
	s_addc_u32 s45, s37, 0
	s_cmp_eq_u32 s17, s44
	s_cselect_b32 s45, s29, s45
	s_cselect_b32 s44, s28, s46
	s_cselect_b32 s47, s31, s70
	s_cselect_b32 s46, s30, s69
	v_lshl_add_u64 v[166:167], s[36:37], 0, v[186:187]
	s_add_i32 m0, s39, 0xc000
	ds_read_b128 v[146:149], v228
	ds_read_b128 v[150:153], v228 offset:1024
	ds_read_b128 v[154:157], v228 offset:2048
	ds_read_b128 v[158:161], v228 offset:3072
	ds_read_b128 v[162:165], v228 offset:4096
	ds_read_b128 v[190:193], v228 offset:5120
	ds_read_b128 v[194:197], v228 offset:6144
	ds_read_b128 v[198:201], v228 offset:7168
	global_load_lds_dwordx4 v[166:167], off
	v_lshl_add_u64 v[166:167], s[36:37], 0, v[188:189]
	s_add_i32 m0, s39, 0xe000
	v_add_u32_e32 v142, 0x10000, v225
	global_load_lds_dwordx4 v[166:167], off
	ds_read_b128 v[130:133], v142
	ds_read_b128 v[134:137], v142 offset:1024
	ds_read_b128 v[138:141], v142 offset:2048
	ds_read_b128 v[142:145], v142 offset:3072
	v_add_u32_e32 v166, 0x14000, v225
	ds_read_b128 v[202:205], v166
	ds_read_b128 v[230:233], v166 offset:1024
	ds_read_b128 v[234:237], v166 offset:2048
	ds_read_b128 v[238:241], v166 offset:3072
	s_waitcnt vmcnt(8) lgkmcnt(0)
	s_barrier
	v_mfma_f32_16x16x32_bf16 v[124:127], v[130:133], v[146:149], v[124:127]
	v_mfma_f32_16x16x32_bf16 v[120:123], v[138:141], v[146:149], v[120:123]
	v_mfma_f32_16x16x32_bf16 v[112:115], v[130:133], v[154:157], v[112:115]
	v_mfma_f32_16x16x32_bf16 v[104:107], v[138:141], v[154:157], v[104:107]
	v_mfma_f32_16x16x32_bf16 v[96:99], v[130:133], v[162:165], v[96:99]
	v_mfma_f32_16x16x32_bf16 v[88:91], v[138:141], v[162:165], v[88:91]
	v_mfma_f32_16x16x32_bf16 v[80:83], v[130:133], v[194:197], v[80:83]
	v_mfma_f32_16x16x32_bf16 v[72:75], v[138:141], v[194:197], v[72:75]
	v_mfma_f32_16x16x32_bf16 v[124:127], v[134:137], v[150:153], v[124:127]
	v_mfma_f32_16x16x32_bf16 v[120:123], v[142:145], v[150:153], v[120:123]
	v_mfma_f32_16x16x32_bf16 v[112:115], v[134:137], v[158:161], v[112:115]
	v_mfma_f32_16x16x32_bf16 v[104:107], v[142:145], v[158:161], v[104:107]
	v_mfma_f32_16x16x32_bf16 v[96:99], v[134:137], v[190:193], v[96:99]
	v_mfma_f32_16x16x32_bf16 v[88:91], v[142:145], v[190:193], v[88:91]
	v_mfma_f32_16x16x32_bf16 v[80:83], v[134:137], v[198:201], v[80:83]
	v_mfma_f32_16x16x32_bf16 v[72:75], v[142:145], v[198:201], v[72:75]
	v_mfma_f32_16x16x32_bf16 v[116:119], v[202:205], v[146:149], v[116:119]
	v_mfma_f32_16x16x32_bf16 v[108:111], v[234:237], v[146:149], v[108:111]
	v_mfma_f32_16x16x32_bf16 v[100:103], v[202:205], v[154:157], v[100:103]
	v_mfma_f32_16x16x32_bf16 v[92:95], v[234:237], v[154:157], v[92:95]
	v_mfma_f32_16x16x32_bf16 v[84:87], v[202:205], v[162:165], v[84:87]
	v_mfma_f32_16x16x32_bf16 v[76:79], v[234:237], v[162:165], v[76:79]
	v_mfma_f32_16x16x32_bf16 v[68:71], v[202:205], v[194:197], v[68:71]
	v_mfma_f32_16x16x32_bf16 v[64:67], v[234:237], v[194:197], v[64:67]
	v_mfma_f32_16x16x32_bf16 v[116:119], v[230:233], v[150:153], v[116:119]
	v_mfma_f32_16x16x32_bf16 v[108:111], v[238:241], v[150:153], v[108:111]
	v_mfma_f32_16x16x32_bf16 v[100:103], v[230:233], v[158:161], v[100:103]
	v_mfma_f32_16x16x32_bf16 v[92:95], v[238:241], v[158:161], v[92:95]
	v_mfma_f32_16x16x32_bf16 v[84:87], v[230:233], v[190:193], v[84:87]
	v_mfma_f32_16x16x32_bf16 v[76:79], v[238:241], v[190:193], v[76:79]
	v_mfma_f32_16x16x32_bf16 v[68:71], v[230:233], v[198:201], v[68:71]
	v_mfma_f32_16x16x32_bf16 v[64:67], v[238:241], v[198:201], v[64:67]
	s_barrier
	ds_read_b128 v[146:149], v228 offset:16384
	ds_read_b128 v[150:153], v228 offset:17408
	ds_read_b128 v[154:157], v228 offset:18432
	ds_read_b128 v[158:161], v228 offset:19456
	ds_read_b128 v[162:165], v228 offset:20480
	ds_read_b128 v[190:193], v228 offset:21504
	ds_read_b128 v[194:197], v228 offset:22528
	ds_read_b128 v[198:201], v228 offset:23552
	s_add_i32 s71, s57, 0x10000
	v_lshl_add_u64 v[166:167], s[46:47], 0, v[168:169]
	s_mov_b32 m0, s71
	v_lshl_add_u64 v[206:207], s[46:47], 0, v[178:179]
	global_load_lds_dwordx4 v[166:167], off
	s_add_i32 m0, s71, 0x2000
	v_lshl_add_u64 v[242:243], s[44:45], 0, v[174:175]
	global_load_lds_dwordx4 v[206:207], off
	s_mov_b32 m0, s39
	v_lshl_add_u64 v[244:245], s[44:45], 0, v[176:177]
	global_load_lds_dwordx4 v[242:243], off
	s_mov_b32 m0, s54
	s_add_u32 s46, s46, s50
	s_addc_u32 s47, s47, 0
	global_load_lds_dwordx4 v[244:245], off
	s_add_i32 s71, s57, 0x14000
	v_lshl_add_u64 v[246:247], s[46:47], 0, v[168:169]
	s_mov_b32 m0, s71
	v_lshl_add_u64 v[248:249], s[46:47], 0, v[178:179]
	global_load_lds_dwordx4 v[246:247], off
	s_add_i32 m0, s71, 0x2000
	s_nop 0
	global_load_lds_dwordx4 v[248:249], off
	s_waitcnt vmcnt(8) lgkmcnt(0)
	s_barrier
; #define PG8_STAGE(bufoff, gbase, voff) do { _Pragma("unroll") for (int _i = 0; _i < 2; ++_i) \
;         __builtin_amdgcn_global_load_lds((const unsigned*)((const char*)(gbase) + (voff)[_i]), (LAS unsigned*)(lds + (bufoff) + ldsw + _i * 8192), 16, 0, 0); } while (0)
; #define PG8_LDA(dst, b, h) do { _Pragma("unroll") for (int m = 0; m < 4; ++m) _Pragma("unroll") for (int k = 0; k < 2; ++k) dst[m][k] = *(const LAS bf16x8*)(lds + PG8_SA(b, h) + aoff + m * 2048 + k * 1024); } while (0)
; #define PG8_LDB(dst, b, h) do { _Pragma("unroll") for (int n = 0; n < 2; ++n) _Pragma("unroll") for (int k = 0; k < 2; ++k) dst[n][k] = *(const LAS bf16x8*)(lds + PG8_SB(b, h) + boff + n * 2048 + k * 1024); } while (0)
; #define PG8_MMA(ai, bj, At, Bt) do { __builtin_amdgcn_s_setprio(1); _Pragma("unroll") for (int m = 0; m < 4; ++m) _Pragma("unroll") for (int n = 0; n < 2; ++n) _Pragma("unroll") for (int k = 0; k < 2; ++k) \
;         acc[ai][bj][m][n] = __builtin_amdgcn_mfma_f32_16x16x32_bf16(Bt[n][k], At[m][k], acc[ai][bj][m][n], 0, 0, 0); __builtin_amdgcn_s_setprio(0); } while (0)
; #define PG8_WAIT_V(n) asm volatile("s_waitcnt vmcnt(" #n ")" ::: "memory")
; #define PG8_WAIT_L(n) asm volatile("s_waitcnt lgkmcnt(" #n ")" ::: "memory")
; #define PG8_BAR __builtin_amdgcn_s_barrier()
; #define PG8_SCHED __builtin_amdgcn_sched_barrier(0)
; template <class Epi>
; __device__ __forceinline__ void gemm_phase(LAS unsigned char* lds, const Gemm g, const StaticOrder& S, const Epi& E) {
;     ...
;             PG8_BAR; PG8_WAIT_L(0); PG8_MMA(1, 0, At, B0); PG8_BAR; PG8_SCHED;
;             PG8_STAGE(PG8_SB(0, 1), b2 + hstepB, voffB);
;             PG8_WAIT_V(6); PG8_BAR; PG8_MMA(1, 1, At, B1); PG8_BAR;
;             PG8_LDB(B0, 1, 0); PG8_SCHED; PG8_LDA(At, 1, 0); PG8_STAGE(PG8_SA(0, 1), a2 + hstepA, voffA);
;             PG8_WAIT_L(8); PG8_BAR; PG8_WAIT_L(0); PG8_MMA(0, 0, At, B0); PG8_BAR; PG8_SCHED;
;             PG8_LDB(B1, 1, 1); PG8_STAGE(PG8_SB(1, 0), b3, voffB);
;             PG8_BAR; PG8_WAIT_L(0); PG8_MMA(0, 1, At, B1); PG8_BAR;
	v_mfma_f32_16x16x32_bf16 v[60:63], v[130:133], v[146:149], v[60:63]
	v_mfma_f32_16x16x32_bf16 v[56:59], v[138:141], v[146:149], v[56:59]
	v_mfma_f32_16x16x32_bf16 v[52:55], v[130:133], v[154:157], v[52:55]
	v_mfma_f32_16x16x32_bf16 v[44:47], v[138:141], v[154:157], v[44:47]
	v_mfma_f32_16x16x32_bf16 v[36:39], v[130:133], v[162:165], v[36:39]
	v_mfma_f32_16x16x32_bf16 v[28:31], v[138:141], v[162:165], v[28:31]
	v_mfma_f32_16x16x32_bf16 v[20:23], v[130:133], v[194:197], v[20:23]
	v_mfma_f32_16x16x32_bf16 v[12:15], v[138:141], v[194:197], v[12:15]
	v_mfma_f32_16x16x32_bf16 v[60:63], v[134:137], v[150:153], v[60:63]
	v_mfma_f32_16x16x32_bf16 v[56:59], v[142:145], v[150:153], v[56:59]
	v_mfma_f32_16x16x32_bf16 v[52:55], v[134:137], v[158:161], v[52:55]
	v_mfma_f32_16x16x32_bf16 v[44:47], v[142:145], v[158:161], v[44:47]
	v_mfma_f32_16x16x32_bf16 v[36:39], v[134:137], v[190:193], v[36:39]
	v_mfma_f32_16x16x32_bf16 v[28:31], v[142:145], v[190:193], v[28:31]
	v_mfma_f32_16x16x32_bf16 v[20:23], v[134:137], v[198:201], v[20:23]
	v_mfma_f32_16x16x32_bf16 v[12:15], v[142:145], v[198:201], v[12:15]
	v_mfma_f32_16x16x32_bf16 v[48:51], v[202:205], v[146:149], v[48:51]
	v_mfma_f32_16x16x32_bf16 v[40:43], v[234:237], v[146:149], v[40:43]
	v_mfma_f32_16x16x32_bf16 v[32:35], v[202:205], v[154:157], v[32:35]
	v_mfma_f32_16x16x32_bf16 v[24:27], v[234:237], v[154:157], v[24:27]
	v_mfma_f32_16x16x32_bf16 v[16:19], v[202:205], v[162:165], v[16:19]
	v_mfma_f32_16x16x32_bf16 v[8:11], v[234:237], v[162:165], v[8:11]
	v_mfma_f32_16x16x32_bf16 v[4:7], v[202:205], v[194:197], v[4:7]
	v_mfma_f32_16x16x32_bf16 v[0:3], v[234:237], v[194:197], v[0:3]
	v_mfma_f32_16x16x32_bf16 v[48:51], v[230:233], v[150:153], v[48:51]
	v_mfma_f32_16x16x32_bf16 v[40:43], v[238:241], v[150:153], v[40:43]
	v_mfma_f32_16x16x32_bf16 v[32:35], v[230:233], v[158:161], v[32:35]
	v_mfma_f32_16x16x32_bf16 v[24:27], v[238:241], v[158:161], v[24:27]
	v_mfma_f32_16x16x32_bf16 v[16:19], v[230:233], v[190:193], v[16:19]
	v_mfma_f32_16x16x32_bf16 v[8:11], v[238:241], v[190:193], v[8:11]
	v_mfma_f32_16x16x32_bf16 v[4:7], v[230:233], v[198:201], v[4:7]
	v_mfma_f32_16x16x32_bf16 v[0:3], v[238:241], v[198:201], v[0:3]
	s_barrier
	s_add_u32 s44, s44, s74
	s_addc_u32 s45, s45, 0
	s_mov_b32 m0, s55
	v_lshl_add_u64 v[250:251], s[44:45], 0, v[174:175]
	ds_read_b128 v[146:149], v228 offset:32768
	ds_read_b128 v[150:153], v228 offset:33792
	ds_read_b128 v[154:157], v228 offset:34816
	ds_read_b128 v[158:161], v228 offset:35840
	ds_read_b128 v[162:165], v228 offset:36864
	ds_read_b128 v[190:193], v228 offset:37888
	ds_read_b128 v[194:197], v228 offset:38912
	ds_read_b128 v[198:201], v228 offset:39936
	global_load_lds_dwordx4 v[250:251], off
	v_lshl_add_u64 v[250:251], s[44:45], 0, v[176:177]
	s_mov_b32 m0, s3
	v_add_u32_e32 v142, 0x18000, v225
	global_load_lds_dwordx4 v[250:251], off
	ds_read_b128 v[130:133], v142
	ds_read_b128 v[134:137], v142 offset:1024
	ds_read_b128 v[138:141], v142 offset:2048
	ds_read_b128 v[142:145], v142 offset:3072
	v_add_u32_e32 v172, 0x1c000, v225
	ds_read_b128 v[202:205], v172
	ds_read_b128 v[230:233], v172 offset:1024
	ds_read_b128 v[234:237], v172 offset:2048
	ds_read_b128 v[238:241], v172 offset:3072
	s_waitcnt vmcnt(8) lgkmcnt(0)
	s_barrier
	v_mfma_f32_16x16x32_bf16 v[124:127], v[130:133], v[146:149], v[124:127]
	v_mfma_f32_16x16x32_bf16 v[120:123], v[138:141], v[146:149], v[120:123]
	v_mfma_f32_16x16x32_bf16 v[112:115], v[130:133], v[154:157], v[112:115]
	v_mfma_f32_16x16x32_bf16 v[104:107], v[138:141], v[154:157], v[104:107]
	v_mfma_f32_16x16x32_bf16 v[96:99], v[130:133], v[162:165], v[96:99]
	v_mfma_f32_16x16x32_bf16 v[88:91], v[138:141], v[162:165], v[88:91]
	v_mfma_f32_16x16x32_bf16 v[80:83], v[130:133], v[194:197], v[80:83]
	v_mfma_f32_16x16x32_bf16 v[72:75], v[138:141], v[194:197], v[72:75]
	v_mfma_f32_16x16x32_bf16 v[124:127], v[134:137], v[150:153], v[124:127]
	v_mfma_f32_16x16x32_bf16 v[120:123], v[142:145], v[150:153], v[120:123]
	v_mfma_f32_16x16x32_bf16 v[112:115], v[134:137], v[158:161], v[112:115]
	v_mfma_f32_16x16x32_bf16 v[104:107], v[142:145], v[158:161], v[104:107]
	v_mfma_f32_16x16x32_bf16 v[96:99], v[134:137], v[190:193], v[96:99]
	v_mfma_f32_16x16x32_bf16 v[88:91], v[142:145], v[190:193], v[88:91]
	v_mfma_f32_16x16x32_bf16 v[80:83], v[134:137], v[198:201], v[80:83]
	v_mfma_f32_16x16x32_bf16 v[72:75], v[142:145], v[198:201], v[72:75]
	v_mfma_f32_16x16x32_bf16 v[116:119], v[202:205], v[146:149], v[116:119]
	v_mfma_f32_16x16x32_bf16 v[108:111], v[234:237], v[146:149], v[108:111]
	v_mfma_f32_16x16x32_bf16 v[100:103], v[202:205], v[154:157], v[100:103]
	v_mfma_f32_16x16x32_bf16 v[92:95], v[234:237], v[154:157], v[92:95]
	v_mfma_f32_16x16x32_bf16 v[84:87], v[202:205], v[162:165], v[84:87]
	v_mfma_f32_16x16x32_bf16 v[76:79], v[234:237], v[162:165], v[76:79]
	v_mfma_f32_16x16x32_bf16 v[68:71], v[202:205], v[194:197], v[68:71]
	v_mfma_f32_16x16x32_bf16 v[64:67], v[234:237], v[194:197], v[64:67]
	v_mfma_f32_16x16x32_bf16 v[116:119], v[230:233], v[150:153], v[116:119]
	v_mfma_f32_16x16x32_bf16 v[108:111], v[238:241], v[150:153], v[108:111]
	v_mfma_f32_16x16x32_bf16 v[100:103], v[230:233], v[158:161], v[100:103]
	v_mfma_f32_16x16x32_bf16 v[92:95], v[238:241], v[158:161], v[92:95]
	v_mfma_f32_16x16x32_bf16 v[84:87], v[230:233], v[190:193], v[84:87]
	v_mfma_f32_16x16x32_bf16 v[76:79], v[238:241], v[190:193], v[76:79]
	v_mfma_f32_16x16x32_bf16 v[68:71], v[230:233], v[198:201], v[68:71]
	v_mfma_f32_16x16x32_bf16 v[64:67], v[238:241], v[198:201], v[64:67]
	s_barrier
; #define PG8_STAGE(bufoff, gbase, voff) do { _Pragma("unroll") for (int _i = 0; _i < 2; ++_i) \
;         __builtin_amdgcn_global_load_lds((const unsigned*)((const char*)(gbase) + (voff)[_i]), (LAS unsigned*)(lds + (bufoff) + ldsw + _i * 8192), 16, 0, 0); } while (0)
; #define PG8_LDA(dst, b, h) do { _Pragma("unroll") for (int m = 0; m < 4; ++m) _Pragma("unroll") for (int k = 0; k < 2; ++k) dst[m][k] = *(const LAS bf16x8*)(lds + PG8_SA(b, h) + aoff + m * 2048 + k * 1024); } while (0)
; #define PG8_MMA(ai, bj, At, Bt) do { __builtin_amdgcn_s_setprio(1); _Pragma("unroll") for (int m = 0; m < 4; ++m) _Pragma("unroll") for (int n = 0; n < 2; ++n) _Pragma("unroll") for (int k = 0; k < 2; ++k) \
;         acc[ai][bj][m][n] = __builtin_amdgcn_mfma_f32_16x16x32_bf16(Bt[n][k], At[m][k], acc[ai][bj][m][n], 0, 0, 0); __builtin_amdgcn_s_setprio(0); } while (0)
; #define PG8_WAIT_V(n) asm volatile("s_waitcnt vmcnt(" #n ")" ::: "memory")
; #define PG8_WAIT_L(n) asm volatile("s_waitcnt lgkmcnt(" #n ")" ::: "memory")
; #define PG8_BAR __builtin_amdgcn_s_barrier()
; #define PG8_SCHED __builtin_amdgcn_sched_barrier(0)
; template <class Epi>
; __device__ __forceinline__ void gemm_phase(LAS unsigned char* lds, const Gemm g, const StaticOrder& S, const Epi& E) {
;     ...
;             PG8_LDA(At, 1, 1); PG8_STAGE(PG8_SA(1, 0), a3, voffA);
;             PG8_BAR; PG8_WAIT_L(0); PG8_MMA(1, 0, At, B0); PG8_BAR; PG8_SCHED;
;             PG8_STAGE(PG8_SB(1, 1), b3 + hstepB, voffB);
;             PG8_WAIT_V(6); PG8_BAR; PG8_MMA(1, 1, At, B1); PG8_BAR;
;     __device__ __forceinline__ void operator()(const f32x4 (&acc)[2][2][4][2], const Unit& u, int wr, int wc, int fr, int fq, const LAS float* rsl) const {
;     ...
;                 const int row = row0 + ai * 128 + m * 16;
;                 const float rstd = rsqrtf(rs[ai][m] * (1.f / 1024.f) + EPS);
;                 bf16_t* rp = proj + (size_t)row * PW + wc * 32 + 8 * fq;
;                 if (pn < 9) {
; #pragma unroll
;                     for (int bj = 0; bj < 2; ++bj) store8bf_nt(rp + pn * 256 + bj * 128, acc[ai][bj][m][0] * rstd, acc[ai][bj][m][1] * rstd);
	ds_read_b128 v[146:149], v228 offset:49152
	ds_read_b128 v[150:153], v228 offset:50176
	ds_read_b128 v[154:157], v228 offset:51200
	ds_read_b128 v[158:161], v228 offset:52224
	ds_read_b128 v[162:165], v228 offset:53248
	ds_read_b128 v[190:193], v228 offset:54272
	ds_read_b128 v[194:197], v228 offset:55296
	ds_read_b128 v[198:201], v228 offset:56320
	s_add_i32 s44, s57, 0x18000
	v_lshl_add_u64 v[166:167], v[166:167], 0, s[88:89]
	s_mov_b32 m0, s44
	v_lshl_add_u64 v[206:207], v[206:207], 0, s[88:89]
	global_load_lds_dwordx4 v[166:167], off
	s_add_i32 m0, s44, 0x2000
	v_lshl_add_u64 v[242:243], v[242:243], 0, s[88:89]
	global_load_lds_dwordx4 v[206:207], off
	s_mov_b32 m0, s60
	v_lshl_add_u64 v[244:245], v[244:245], 0, s[88:89]
	global_load_lds_dwordx4 v[242:243], off
	s_mov_b32 m0, s61
	s_add_i32 s44, s57, 0x1c000
	v_lshl_add_u64 v[246:247], v[246:247], 0, s[88:89]
	global_load_lds_dwordx4 v[244:245], off
	s_mov_b32 m0, s44
	v_lshl_add_u64 v[248:249], v[248:249], 0, s[88:89]
	global_load_lds_dwordx4 v[246:247], off
	s_add_i32 m0, s44, 0x2000
	s_nop 0
	global_load_lds_dwordx4 v[248:249], off
	s_cmp_lt_u32 s35, s16
	s_cbranch_scc1 .Le0_skip
	s_cmp_eq_u32 s32, 0
	s_cbranch_scc1 .Le0_skip
	v_lshl_add_u32 v172, s20, 2, v226
	ds_read2_b32 v[250:251], v172 offset1:16
	ds_read2_b32 v[252:253], v172 offset0:32 offset1:48
	v_add_u32_e32 v242, s34, v171
	v_mad_i64_i32 v[244:245], s[46:47], v242, s0, v[182:183]
	s_lshl_b32 s46, s48, 9
	s_mov_b32 s47, 0
	v_lshl_add_u64 v[244:245], v[244:245], 0, s[46:47]
	s_waitcnt lgkmcnt(0)
	v_fmamk_f32 v246, v250, 0x3a800000, v209
	v_mul_f32_e32 v247, 0x4b800000, v246
	v_cmp_gt_f32_e32 vcc, s81, v246
	s_nop 1
	v_cndmask_b32_e32 v246, v246, v247, vcc
	v_rsq_f32_e32 v246, v246
	s_nop 0
	v_mul_f32_e32 v247, 0x45800000, v246
	v_cndmask_b32_e32 v246, v246, v247, vcc
	v_pk_mul_f32 v[124:125], v[124:125], v[246:247] op_sel_hi:[1,0]
	v_pk_mul_f32 v[126:127], v[126:127], v[246:247] op_sel_hi:[1,0]
	v_pk_mul_f32 v[120:121], v[120:121], v[246:247] op_sel_hi:[1,0]
	v_pk_mul_f32 v[122:123], v[122:123], v[246:247] op_sel_hi:[1,0]
	v_cvt_pk_bf16_f32 v124, v124, v125
	v_cvt_pk_bf16_f32 v125, v126, v127
	v_cvt_pk_bf16_f32 v126, v120, v121
	v_cvt_pk_bf16_f32 v127, v122, v123
	global_store_dwordx4 v[244:245], v[124:127], off nt
	v_pk_mul_f32 v[116:117], v[116:117], v[246:247] op_sel_hi:[1,0]
	v_pk_mul_f32 v[118:119], v[118:119], v[246:247] op_sel_hi:[1,0]
	v_pk_mul_f32 v[108:109], v[108:109], v[246:247] op_sel_hi:[1,0]
	v_pk_mul_f32 v[110:111], v[110:111], v[246:247] op_sel_hi:[1,0]
	v_cvt_pk_bf16_f32 v116, v116, v117
	v_cvt_pk_bf16_f32 v117, v118, v119
	v_cvt_pk_bf16_f32 v118, v108, v109
	v_cvt_pk_bf16_f32 v119, v110, v111
	global_store_dwordx4 v[244:245], v[116:119], off offset:256 nt
	v_add_co_u32_e32 v244, vcc, 0x22000, v244
	s_nop 1
	v_addc_co_u32_e32 v245, vcc, 0, v245, vcc
	v_fmamk_f32 v246, v251, 0x3a800000, v209
	v_mul_f32_e32 v247, 0x4b800000, v246
	v_cmp_gt_f32_e32 vcc, s81, v246
	s_nop 1
	v_cndmask_b32_e32 v246, v246, v247, vcc
	v_rsq_f32_e32 v246, v246
	s_nop 0
	v_mul_f32_e32 v247, 0x45800000, v246
	v_cndmask_b32_e32 v246, v246, v247, vcc
	v_pk_mul_f32 v[112:113], v[112:113], v[246:247] op_sel_hi:[1,0]
	v_pk_mul_f32 v[114:115], v[114:115], v[246:247] op_sel_hi:[1,0]
	v_pk_mul_f32 v[104:105], v[104:105], v[246:247] op_sel_hi:[1,0]
	v_pk_mul_f32 v[106:107], v[106:107], v[246:247] op_sel_hi:[1,0]
	v_cvt_pk_bf16_f32 v112, v112, v113
	v_cvt_pk_bf16_f32 v113, v114, v115
	v_cvt_pk_bf16_f32 v114, v104, v105
	v_cvt_pk_bf16_f32 v115, v106, v107
	global_store_dwordx4 v[244:245], v[112:115], off nt
	v_pk_mul_f32 v[100:101], v[100:101], v[246:247] op_sel_hi:[1,0]
	v_pk_mul_f32 v[102:103], v[102:103], v[246:247] op_sel_hi:[1,0]
	v_pk_mul_f32 v[92:93], v[92:93], v[246:247] op_sel_hi:[1,0]
	v_pk_mul_f32 v[94:95], v[94:95], v[246:247] op_sel_hi:[1,0]
	v_cvt_pk_bf16_f32 v100, v100, v101
	v_cvt_pk_bf16_f32 v101, v102, v103
	v_cvt_pk_bf16_f32 v102, v92, v93
	v_cvt_pk_bf16_f32 v103, v94, v95
	global_store_dwordx4 v[244:245], v[100:103], off offset:256 nt
	v_add_co_u32_e32 v244, vcc, 0x22000, v244
	s_nop 1
	v_addc_co_u32_e32 v245, vcc, 0, v245, vcc
	v_fmamk_f32 v246, v252, 0x3a800000, v209
	v_mul_f32_e32 v247, 0x4b800000, v246
	v_cmp_gt_f32_e32 vcc, s81, v246
	s_nop 1
	v_cndmask_b32_e32 v246, v246, v247, vcc
	v_rsq_f32_e32 v246, v246
	s_nop 0
	v_mul_f32_e32 v247, 0x45800000, v246
	v_cndmask_b32_e32 v246, v246, v247, vcc
	v_pk_mul_f32 v[96:97], v[96:97], v[246:247] op_sel_hi:[1,0]
	v_pk_mul_f32 v[98:99], v[98:99], v[246:247] op_sel_hi:[1,0]
	v_pk_mul_f32 v[88:89], v[88:89], v[246:247] op_sel_hi:[1,0]
	v_pk_mul_f32 v[90:91], v[90:91], v[246:247] op_sel_hi:[1,0]
	v_cvt_pk_bf16_f32 v96, v96, v97
	v_cvt_pk_bf16_f32 v97, v98, v99
	v_cvt_pk_bf16_f32 v98, v88, v89
	v_cvt_pk_bf16_f32 v99, v90, v91
	global_store_dwordx4 v[244:245], v[96:99], off nt
	v_pk_mul_f32 v[84:85], v[84:85], v[246:247] op_sel_hi:[1,0]
	v_pk_mul_f32 v[86:87], v[86:87], v[246:247] op_sel_hi:[1,0]
	v_pk_mul_f32 v[76:77], v[76:77], v[246:247] op_sel_hi:[1,0]
	v_pk_mul_f32 v[78:79], v[78:79], v[246:247] op_sel_hi:[1,0]
	v_cvt_pk_bf16_f32 v84, v84, v85
	v_cvt_pk_bf16_f32 v85, v86, v87
	v_cvt_pk_bf16_f32 v86, v76, v77
	v_cvt_pk_bf16_f32 v87, v78, v79
	global_store_dwordx4 v[244:245], v[84:87], off offset:256 nt
	v_add_co_u32_e32 v244, vcc, 0x22000, v244
	s_nop 1
	v_addc_co_u32_e32 v245, vcc, 0, v245, vcc
	v_fmamk_f32 v246, v253, 0x3a800000, v209
	v_mul_f32_e32 v247, 0x4b800000, v246
	v_cmp_gt_f32_e32 vcc, s81, v246
	s_nop 1
	v_cndmask_b32_e32 v246, v246, v247, vcc
	v_rsq_f32_e32 v246, v246
	s_nop 0
	v_mul_f32_e32 v247, 0x45800000, v246
	v_cndmask_b32_e32 v246, v246, v247, vcc
	v_pk_mul_f32 v[80:81], v[80:81], v[246:247] op_sel_hi:[1,0]
	v_pk_mul_f32 v[82:83], v[82:83], v[246:247] op_sel_hi:[1,0]
	v_pk_mul_f32 v[72:73], v[72:73], v[246:247] op_sel_hi:[1,0]
	v_pk_mul_f32 v[74:75], v[74:75], v[246:247] op_sel_hi:[1,0]
	v_cvt_pk_bf16_f32 v80, v80, v81
	v_cvt_pk_bf16_f32 v81, v82, v83
	v_cvt_pk_bf16_f32 v82, v72, v73
	v_cvt_pk_bf16_f32 v83, v74, v75
	global_store_dwordx4 v[244:245], v[80:83], off nt
	v_pk_mul_f32 v[68:69], v[68:69], v[246:247] op_sel_hi:[1,0]
	v_pk_mul_f32 v[70:71], v[70:71], v[246:247] op_sel_hi:[1,0]
	v_pk_mul_f32 v[64:65], v[64:65], v[246:247] op_sel_hi:[1,0]
	v_pk_mul_f32 v[66:67], v[66:67], v[246:247] op_sel_hi:[1,0]
	v_cvt_pk_bf16_f32 v68, v68, v69
	v_cvt_pk_bf16_f32 v69, v70, v71
	v_cvt_pk_bf16_f32 v70, v64, v65
	v_cvt_pk_bf16_f32 v71, v66, v67
	global_store_dwordx4 v[244:245], v[68:71], off offset:256 nt
	s_waitcnt vmcnt(16) lgkmcnt(0)
	s_barrier
	s_branch .Le0_join
; #define PG8_STAGE(bufoff, gbase, voff) do { _Pragma("unroll") for (int _i = 0; _i < 2; ++_i) \
;         __builtin_amdgcn_global_load_lds((const unsigned*)((const char*)(gbase) + (voff)[_i]), (LAS unsigned*)(lds + (bufoff) + ldsw + _i * 8192), 16, 0, 0); } while (0)
; #define PG8_MMA(ai, bj, At, Bt) do { __builtin_amdgcn_s_setprio(1); _Pragma("unroll") for (int m = 0; m < 4; ++m) _Pragma("unroll") for (int n = 0; n < 2; ++n) _Pragma("unroll") for (int k = 0; k < 2; ++k) \
;         acc[ai][bj][m][n] = __builtin_amdgcn_mfma_f32_16x16x32_bf16(Bt[n][k], At[m][k], acc[ai][bj][m][n], 0, 0, 0); __builtin_amdgcn_s_setprio(0); } while (0)
; #define PG8_WAIT_V(n) asm volatile("s_waitcnt vmcnt(" #n ")" ::: "memory")
; #define PG8_WAIT_L(n) asm volatile("s_waitcnt lgkmcnt(" #n ")" ::: "memory")
; #define PG8_BAR __builtin_amdgcn_s_barrier()
; #define PG8_SCHED __builtin_amdgcn_sched_barrier(0)
; template <class Epi>
; __device__ __forceinline__ void gemm_phase(LAS unsigned char* lds, const Gemm g, const StaticOrder& S, const Epi& E) {
;     ...
;             PG8_BAR; PG8_WAIT_L(0); PG8_MMA(1, 0, At, B0); PG8_BAR; PG8_SCHED;
;             PG8_STAGE(PG8_SB(1, 1), b3 + hstepB, voffB);
;             PG8_WAIT_V(6); PG8_BAR; PG8_MMA(1, 1, At, B1); PG8_BAR;
.Le0_skip:
	s_waitcnt vmcnt(8) lgkmcnt(0)
	s_barrier
.Le0_join:
	v_mfma_f32_16x16x32_bf16 v[60:63], v[130:133], v[146:149], v[60:63]
	v_mfma_f32_16x16x32_bf16 v[56:59], v[138:141], v[146:149], v[56:59]
	v_mfma_f32_16x16x32_bf16 v[52:55], v[130:133], v[154:157], v[52:55]
	v_mfma_f32_16x16x32_bf16 v[44:47], v[138:141], v[154:157], v[44:47]
	s_add_u32 s36, s36, 0x100
	s_addc_u32 s37, s37, 0
	s_add_u32 s69, s69, 0x100
	s_addc_u32 s70, s70, 0
	s_cmp_ge_u32 s35, s16
	s_mov_b32 s44, s35
	v_mfma_f32_16x16x32_bf16 v[36:39], v[130:133], v[162:165], v[36:39]
	v_mfma_f32_16x16x32_bf16 v[28:31], v[138:141], v[162:165], v[28:31]
	v_mfma_f32_16x16x32_bf16 v[20:23], v[130:133], v[194:197], v[20:23]
	v_mfma_f32_16x16x32_bf16 v[12:15], v[138:141], v[194:197], v[12:15]
	v_mfma_f32_16x16x32_bf16 v[60:63], v[134:137], v[150:153], v[60:63]
	v_mfma_f32_16x16x32_bf16 v[56:59], v[142:145], v[150:153], v[56:59]
	v_mfma_f32_16x16x32_bf16 v[52:55], v[134:137], v[158:161], v[52:55]
	v_mfma_f32_16x16x32_bf16 v[44:47], v[142:145], v[158:161], v[44:47]
	v_mfma_f32_16x16x32_bf16 v[36:39], v[134:137], v[190:193], v[36:39]
	v_mfma_f32_16x16x32_bf16 v[28:31], v[142:145], v[190:193], v[28:31]
	v_mfma_f32_16x16x32_bf16 v[20:23], v[134:137], v[198:201], v[20:23]
	v_mfma_f32_16x16x32_bf16 v[12:15], v[142:145], v[198:201], v[12:15]
	v_mfma_f32_16x16x32_bf16 v[48:51], v[202:205], v[146:149], v[48:51]
	v_mfma_f32_16x16x32_bf16 v[40:43], v[234:237], v[146:149], v[40:43]
	v_mfma_f32_16x16x32_bf16 v[32:35], v[202:205], v[154:157], v[32:35]
	v_mfma_f32_16x16x32_bf16 v[24:27], v[234:237], v[154:157], v[24:27]
	v_mfma_f32_16x16x32_bf16 v[16:19], v[202:205], v[162:165], v[16:19]
	v_mfma_f32_16x16x32_bf16 v[8:11], v[234:237], v[162:165], v[8:11]
	v_mfma_f32_16x16x32_bf16 v[4:7], v[202:205], v[194:197], v[4:7]
	v_mfma_f32_16x16x32_bf16 v[0:3], v[234:237], v[194:197], v[0:3]
	v_mfma_f32_16x16x32_bf16 v[48:51], v[230:233], v[150:153], v[48:51]
	v_mfma_f32_16x16x32_bf16 v[40:43], v[238:241], v[150:153], v[40:43]
	v_mfma_f32_16x16x32_bf16 v[32:35], v[230:233], v[158:161], v[32:35]
	v_mfma_f32_16x16x32_bf16 v[24:27], v[238:241], v[158:161], v[24:27]
	v_mfma_f32_16x16x32_bf16 v[16:19], v[230:233], v[190:193], v[16:19]
	v_mfma_f32_16x16x32_bf16 v[8:11], v[238:241], v[190:193], v[8:11]
	v_mfma_f32_16x16x32_bf16 v[4:7], v[230:233], v[198:201], v[4:7]
	v_mfma_f32_16x16x32_bf16 v[0:3], v[238:241], v[198:201], v[0:3]
	s_barrier
	s_cbranch_scc1 .LBB0_119

; #define LAS __attribute__((address_space(3)))
;     __device__ __forceinline__ void operator()(const f32x4 (&acc)[2][2][4][2], const Unit& u, int wr, int wc, int fr, int fq, const LAS float* rsl) const {
;         const int row0 = u.pm * 256 + wr * 64 + fr, pn = u.pn;
;         float rs[2][4];
; #pragma unroll
;         for (int ai = 0; ai < 2; ++ai)
; #pragma unroll
;             for (int m = 0; m < 4; ++m) rs[ai][m] = rsl[wr * 64 + fr + ai * 128 + m * 16];
; #pragma unroll
;         for (int ai = 0; ai < 2; ++ai)
; #pragma unroll
;             for (int m = 0; m < 4; ++m) {
;                 const int row = row0 + ai * 128 + m * 16;
;                 const float rstd = rsqrtf(rs[ai][m] * (1.f / 1024.f) + EPS);
;                 bf16_t* rp = proj + (size_t)row * PW + wc * 32 + 8 * fq;
;                 if (pn < 9) {
; #pragma unroll
;                     for (int bj = 0; bj < 2; ++bj) store8bf_nt(rp + pn * 256 + bj * 128, acc[ai][bj][m][0] * rstd, acc[ai][bj][m][1] * rstd);
.LBB0_237:
	s_andn2_b64 vcc, exec, s[36:37]
	s_cbranch_vccnz .LBB0_108
	s_cmp_eq_u32 s1, 1
	s_mov_b64 s[36:37], -1
	s_cbranch_scc1 .LBB0_352
	v_lshl_add_u32 v128, s20, 2, v226
	ds_read2_b32 v[136:137], v128 offset1:16
	ds_read2_b32 v[134:135], v128 offset0:32 offset1:48
	ds_read2_b32 v[132:133], v128 offset0:128 offset1:144
	ds_read2_b32 v[130:131], v128 offset0:160 offset1:176
	s_add_i32 s35, s48, -9
	s_cmp_lt_u32 s35, 16
	s_cbranch_scc1 .Lepi_sc
	s_waitcnt lgkmcnt(0)
	s_cmp_eq_u32 s32, 0
	s_cbranch_scc1 .Lplain_full
	v_add_u32_e32 v128, s34, v171
	s_mov_b64 s[44:45], 0
	s_mov_b64 s[70:71], 0
	s_mov_b64 s[36:37], 0
	s_lshl_b32 s35, s48, 7
	s_lshl_b32 s72, s48, 8
	s_ashr_i32 s73, s72, 31
	s_mov_b64 s[46:47], -1
	s_branch .LBB0_295
.Lplain_full:
	s_cmp_gt_i32 s48, 8
	v_fmamk_f32 v129, v136, 0x3a800000, v209
	v_mul_f32_e32 v136, 0x4b800000, v129
	v_cmp_gt_f32_e32 vcc, s81, v129
	v_add_u32_e32 v128, s34, v171
	s_cselect_b64 s[44:45], -1, 0
	v_cndmask_b32_e32 v129, v129, v136, vcc
	v_rsq_f32_e32 v129, v129
	s_cmp_gt_u32 s48, 16
	s_cselect_b64 s[70:71], -1, 0
	s_cmp_gt_u32 s48, 24
	v_mul_f32_e32 v136, 0x45800000, v129
	v_mad_i64_i32 v[138:139], s[46:47], v128, s0, v[182:183]
	s_cselect_b64 s[36:37], -1, 0
	s_lshl_b32 s35, s48, 7
	v_cndmask_b32_e32 v136, v129, v136, vcc
	v_ashrrev_i32_e32 v129, 31, v128
	s_mov_b64 s[46:47], -1
	s_and_b64 vcc, exec, s[44:45]
	s_cbranch_vccz .LBB0_251
	s_and_b64 vcc, exec, s[70:71]
	s_cbranch_vccz .LBB0_248
	s_and_b64 vcc, exec, s[36:37]
	s_cbranch_vccz .LBB0_245
	s_and_saveexec_b64 s[46:47], s[26:27]
	s_cbranch_execz .LBB0_244
	v_lshlrev_b64 v[140:141], 6, v[128:129]
	v_lshl_add_u64 v[148:149], v[184:185], 0, v[140:141]
	v_pk_mul_f32 v[146:147], v[126:127], v[136:137] op_sel_hi:[1,0]
	v_pk_mul_f32 v[144:145], v[124:125], v[136:137] op_sel_hi:[1,0]
	v_pk_mul_f32 v[142:143], v[122:123], v[136:137] op_sel_hi:[1,0]
	v_pk_mul_f32 v[140:141], v[120:121], v[136:137] op_sel_hi:[1,0]
	global_store_dwordx4 v[148:149], v[144:147], off
	global_store_dwordx4 v[148:149], v[140:143], off offset:16
